# adds E18 (two unit-start full drains removed) and E19 (band attention step 0 skipped by waves that see nothing of key tile 0), stacked on E16
# speedup vs baseline: 1.0176x; 1.0002x over previous
.LBB0_406:
	s_add_u32 s2, s2, 0x80
	s_addc_u32 s3, s3, 0
	s_add_u32 s34, s28, 0x100
	s_addc_u32 s35, s29, 0
	s_mov_b32 s28, 0
	s_add_i32 s43, s28, 2
	s_add_u32 s44, s2, 0x80
	s_addc_u32 s29, s3, 0
	s_add_i32 s46, 0, 0x10000
	s_cmp_eq_u32 s68, s28
	s_cselect_b32 s29, s1, s29
	s_cselect_b32 s28, s0, s44
	s_cselect_b32 s45, s61, s35
	s_cselect_b32 s44, s60, s34
	s_add_i32 s47, 0, 0x14000
	v_add_u32_e32 v140, s46, v241
	v_add_u32_e32 v156, s47, v241
	ds_read_b128 v[128:131], v140
	ds_read_b128 v[132:135], v140 offset:1024
	ds_read_b128 v[136:139], v140 offset:2048
	ds_read_b128 v[140:143], v140 offset:3072
	ds_read_b128 v[144:147], v156
	ds_read_b128 v[148:151], v156 offset:1024
	ds_read_b128 v[152:155], v156 offset:2048
	ds_read_b128 v[156:159], v156 offset:3072
	v_lshl_add_u64 v[194:195], s[2:3], 0, v[210:211]
	s_add_i32 m0, s22, 0xc000
	ds_read_b128 v[160:163], v243
	ds_read_b128 v[164:167], v243 offset:1024
	ds_read_b128 v[168:171], v243 offset:2048
	ds_read_b128 v[172:175], v243 offset:3072
	ds_read_b128 v[176:179], v243 offset:4096
	ds_read_b128 v[180:183], v243 offset:5120
	ds_read_b128 v[184:187], v243 offset:6144
	ds_read_b128 v[188:191], v243 offset:7168
	global_load_lds_dwordx4 v[194:195], off
	v_lshl_add_u64 v[194:195], s[2:3], 0, v[212:213]
	s_add_i32 m0, s22, 0xe000
	s_nop 0
	global_load_lds_dwordx4 v[194:195], off
	s_waitcnt vmcnt(8)
	s_waitcnt lgkmcnt(0)
	s_barrier
	s_setprio 1
	s_waitcnt lgkmcnt(0)
	v_mfma_f32_16x16x32_bf16 v[124:127], v[128:131], v[160:163], 0
	v_mfma_f32_16x16x32_bf16 v[120:123], v[136:139], v[160:163], 0
	v_mfma_f32_16x16x32_bf16 v[108:111], v[128:131], v[168:171], 0
	v_mfma_f32_16x16x32_bf16 v[104:107], v[136:139], v[168:171], 0
	v_mfma_f32_16x16x32_bf16 v[92:95], v[128:131], v[176:179], 0
	v_mfma_f32_16x16x32_bf16 v[88:91], v[136:139], v[176:179], 0
	v_mfma_f32_16x16x32_bf16 v[76:79], v[128:131], v[184:187], 0
	v_mfma_f32_16x16x32_bf16 v[72:75], v[136:139], v[184:187], 0
	v_mfma_f32_16x16x32_bf16 v[124:127], v[132:135], v[164:167], v[124:127]
	v_mfma_f32_16x16x32_bf16 v[120:123], v[140:143], v[164:167], v[120:123]
	v_mfma_f32_16x16x32_bf16 v[108:111], v[132:135], v[172:175], v[108:111]
	v_mfma_f32_16x16x32_bf16 v[104:107], v[140:143], v[172:175], v[104:107]
	v_mfma_f32_16x16x32_bf16 v[92:95], v[132:135], v[180:183], v[92:95]
	v_mfma_f32_16x16x32_bf16 v[88:91], v[140:143], v[180:183], v[88:91]
	v_mfma_f32_16x16x32_bf16 v[76:79], v[132:135], v[188:191], v[76:79]
	v_mfma_f32_16x16x32_bf16 v[72:75], v[140:143], v[188:191], v[72:75]
	s_setprio 0
	s_setprio 1
	v_mfma_f32_16x16x32_bf16 v[116:119], v[144:147], v[160:163], 0
	v_mfma_f32_16x16x32_bf16 v[112:115], v[152:155], v[160:163], 0
	v_mfma_f32_16x16x32_bf16 v[100:103], v[144:147], v[168:171], 0
	v_mfma_f32_16x16x32_bf16 v[96:99], v[152:155], v[168:171], 0
	v_mfma_f32_16x16x32_bf16 v[84:87], v[144:147], v[176:179], 0
	v_mfma_f32_16x16x32_bf16 v[80:83], v[152:155], v[176:179], 0
	v_mfma_f32_16x16x32_bf16 v[68:71], v[144:147], v[184:187], 0
	v_mfma_f32_16x16x32_bf16 v[64:67], v[152:155], v[184:187], 0
	v_mfma_f32_16x16x32_bf16 v[116:119], v[148:151], v[164:167], v[116:119]
	v_mfma_f32_16x16x32_bf16 v[112:115], v[156:159], v[164:167], v[112:115]
	v_mfma_f32_16x16x32_bf16 v[100:103], v[148:151], v[172:175], v[100:103]
	v_mfma_f32_16x16x32_bf16 v[96:99], v[156:159], v[172:175], v[96:99]
	v_mfma_f32_16x16x32_bf16 v[84:87], v[148:151], v[180:183], v[84:87]
	v_mfma_f32_16x16x32_bf16 v[80:83], v[156:159], v[180:183], v[80:83]
	v_mfma_f32_16x16x32_bf16 v[68:71], v[148:151], v[188:191], v[68:71]
	v_mfma_f32_16x16x32_bf16 v[64:67], v[156:159], v[188:191], v[64:67]
	s_setprio 0
	s_barrier
	s_add_i32 s46, s46, s21
	v_lshl_add_u64 v[194:195], s[44:45], 0, v[192:193]
	s_mov_b32 m0, s46
	ds_read_b128 v[160:163], v243 offset:16384
	ds_read_b128 v[164:167], v243 offset:17408
	ds_read_b128 v[168:171], v243 offset:18432
	ds_read_b128 v[172:175], v243 offset:19456
	ds_read_b128 v[176:179], v243 offset:20480
	ds_read_b128 v[180:183], v243 offset:21504
	ds_read_b128 v[184:187], v243 offset:22528
	ds_read_b128 v[188:191], v243 offset:23552
	global_load_lds_dwordx4 v[194:195], off
	s_add_i32 m0, s46, 0x2000
	v_lshl_add_u64 v[196:197], s[44:45], 0, v[204:205]
	s_add_u32 s44, s44, s18
	s_addc_u32 s45, s45, 0
	s_add_i32 s46, s47, s21
	global_load_lds_dwordx4 v[196:197], off
	v_lshl_add_u64 v[198:199], s[44:45], 0, v[192:193]
	s_mov_b32 m0, s46
	v_lshl_add_u64 v[200:201], s[44:45], 0, v[204:205]
	global_load_lds_dwordx4 v[198:199], off
	s_add_i32 m0, s46, 0x2000
	v_lshl_add_u64 v[214:215], s[28:29], 0, v[208:209]
	global_load_lds_dwordx4 v[200:201], off
	s_mov_b32 m0, s22
	v_lshl_add_u64 v[216:217], s[28:29], 0, v[206:207]
	global_load_lds_dwordx4 v[214:215], off
	s_mov_b32 m0, s23
	s_nop 0
	global_load_lds_dwordx4 v[216:217], off
	s_waitcnt vmcnt(8)
	s_waitcnt lgkmcnt(0)
	s_barrier
	s_setprio 1
	s_waitcnt lgkmcnt(0)
	v_mfma_f32_16x16x32_bf16 v[60:63], v[128:131], v[160:163], 0
	v_mfma_f32_16x16x32_bf16 v[56:59], v[136:139], v[160:163], 0
	v_mfma_f32_16x16x32_bf16 v[44:47], v[128:131], v[168:171], 0
	v_mfma_f32_16x16x32_bf16 v[40:43], v[136:139], v[168:171], 0
	v_mfma_f32_16x16x32_bf16 v[28:31], v[128:131], v[176:179], 0
	v_mfma_f32_16x16x32_bf16 v[24:27], v[136:139], v[176:179], 0
	v_mfma_f32_16x16x32_bf16 v[12:15], v[128:131], v[184:187], 0
	v_mfma_f32_16x16x32_bf16 v[8:11], v[136:139], v[184:187], 0
	v_mfma_f32_16x16x32_bf16 v[60:63], v[132:135], v[164:167], v[60:63]
	v_mfma_f32_16x16x32_bf16 v[56:59], v[140:143], v[164:167], v[56:59]
	v_mfma_f32_16x16x32_bf16 v[44:47], v[132:135], v[172:175], v[44:47]
	v_mfma_f32_16x16x32_bf16 v[40:43], v[140:143], v[172:175], v[40:43]
	v_mfma_f32_16x16x32_bf16 v[28:31], v[132:135], v[180:183], v[28:31]
	v_mfma_f32_16x16x32_bf16 v[24:27], v[140:143], v[180:183], v[24:27]
	v_mfma_f32_16x16x32_bf16 v[12:15], v[132:135], v[188:191], v[12:15]
	v_mfma_f32_16x16x32_bf16 v[8:11], v[140:143], v[188:191], v[8:11]
	s_setprio 0
	s_setprio 1
	v_mfma_f32_16x16x32_bf16 v[52:55], v[144:147], v[160:163], 0
	v_mfma_f32_16x16x32_bf16 v[48:51], v[152:155], v[160:163], 0
	v_mfma_f32_16x16x32_bf16 v[36:39], v[144:147], v[168:171], 0
	v_mfma_f32_16x16x32_bf16 v[32:35], v[152:155], v[168:171], 0
	v_mfma_f32_16x16x32_bf16 v[20:23], v[144:147], v[176:179], 0
	v_mfma_f32_16x16x32_bf16 v[16:19], v[152:155], v[176:179], 0
	v_mfma_f32_16x16x32_bf16 v[4:7], v[144:147], v[184:187], 0
	v_mfma_f32_16x16x32_bf16 v[0:3], v[152:155], v[184:187], 0
	v_mfma_f32_16x16x32_bf16 v[52:55], v[148:151], v[164:167], v[52:55]
	v_mfma_f32_16x16x32_bf16 v[48:51], v[156:159], v[164:167], v[48:51]
	v_mfma_f32_16x16x32_bf16 v[36:39], v[148:151], v[172:175], v[36:39]
	v_mfma_f32_16x16x32_bf16 v[32:35], v[156:159], v[172:175], v[32:35]
	v_mfma_f32_16x16x32_bf16 v[20:23], v[148:151], v[180:183], v[20:23]
	v_mfma_f32_16x16x32_bf16 v[16:19], v[156:159], v[180:183], v[16:19]
	v_mfma_f32_16x16x32_bf16 v[4:7], v[148:151], v[188:191], v[4:7]
	v_mfma_f32_16x16x32_bf16 v[0:3], v[156:159], v[188:191], v[0:3]
	s_setprio 0
	s_barrier
	s_add_i32 s44, 0, 0x18000
	s_add_i32 s45, 0, 0x1c000
	v_add_u32_e32 v140, s44, v241
	v_add_u32_e32 v156, s45, v241
	ds_read_b128 v[128:131], v140
	ds_read_b128 v[132:135], v140 offset:1024
	ds_read_b128 v[136:139], v140 offset:2048
	ds_read_b128 v[140:143], v140 offset:3072
	ds_read_b128 v[144:147], v156
	ds_read_b128 v[148:151], v156 offset:1024
	ds_read_b128 v[152:155], v156 offset:2048
	ds_read_b128 v[156:159], v156 offset:3072
	s_add_u32 s28, s28, s18
	s_addc_u32 s29, s29, 0
	s_mov_b32 m0, s62
	v_lshl_add_u64 v[218:219], s[28:29], 0, v[208:209]
	ds_read_b128 v[160:163], v243 offset:32768
	ds_read_b128 v[164:167], v243 offset:33792
	ds_read_b128 v[168:171], v243 offset:34816
	ds_read_b128 v[172:175], v243 offset:35840
	ds_read_b128 v[176:179], v243 offset:36864
	ds_read_b128 v[180:183], v243 offset:37888
	ds_read_b128 v[184:187], v243 offset:38912
	ds_read_b128 v[188:191], v243 offset:39936
	global_load_lds_dwordx4 v[218:219], off
	v_lshl_add_u64 v[218:219], s[28:29], 0, v[206:207]
	s_mov_b32 m0, s63
	s_nop 0
	global_load_lds_dwordx4 v[218:219], off
	s_waitcnt vmcnt(8)
	s_waitcnt lgkmcnt(0)
	s_barrier
	s_setprio 1
	s_waitcnt lgkmcnt(0)
	v_mfma_f32_16x16x32_bf16 v[124:127], v[128:131], v[160:163], v[124:127]
	v_mfma_f32_16x16x32_bf16 v[120:123], v[136:139], v[160:163], v[120:123]
	v_mfma_f32_16x16x32_bf16 v[108:111], v[128:131], v[168:171], v[108:111]
	v_mfma_f32_16x16x32_bf16 v[104:107], v[136:139], v[168:171], v[104:107]
	v_mfma_f32_16x16x32_bf16 v[92:95], v[128:131], v[176:179], v[92:95]
	v_mfma_f32_16x16x32_bf16 v[88:91], v[136:139], v[176:179], v[88:91]
	v_mfma_f32_16x16x32_bf16 v[76:79], v[128:131], v[184:187], v[76:79]
	v_mfma_f32_16x16x32_bf16 v[72:75], v[136:139], v[184:187], v[72:75]
	v_mfma_f32_16x16x32_bf16 v[124:127], v[132:135], v[164:167], v[124:127]
	v_mfma_f32_16x16x32_bf16 v[120:123], v[140:143], v[164:167], v[120:123]
	v_mfma_f32_16x16x32_bf16 v[108:111], v[132:135], v[172:175], v[108:111]
	v_mfma_f32_16x16x32_bf16 v[104:107], v[140:143], v[172:175], v[104:107]
	v_mfma_f32_16x16x32_bf16 v[92:95], v[132:135], v[180:183], v[92:95]
	v_mfma_f32_16x16x32_bf16 v[88:91], v[140:143], v[180:183], v[88:91]
	v_mfma_f32_16x16x32_bf16 v[76:79], v[132:135], v[188:191], v[76:79]
	v_mfma_f32_16x16x32_bf16 v[72:75], v[140:143], v[188:191], v[72:75]
	s_setprio 0
	s_setprio 1
	v_mfma_f32_16x16x32_bf16 v[116:119], v[144:147], v[160:163], v[116:119]
	v_mfma_f32_16x16x32_bf16 v[112:115], v[152:155], v[160:163], v[112:115]
	v_mfma_f32_16x16x32_bf16 v[100:103], v[144:147], v[168:171], v[100:103]
	v_mfma_f32_16x16x32_bf16 v[96:99], v[152:155], v[168:171], v[96:99]
	v_mfma_f32_16x16x32_bf16 v[84:87], v[144:147], v[176:179], v[84:87]
	v_mfma_f32_16x16x32_bf16 v[80:83], v[152:155], v[176:179], v[80:83]
	v_mfma_f32_16x16x32_bf16 v[68:71], v[144:147], v[184:187], v[68:71]
	v_mfma_f32_16x16x32_bf16 v[64:67], v[152:155], v[184:187], v[64:67]
	v_mfma_f32_16x16x32_bf16 v[116:119], v[148:151], v[164:167], v[116:119]
	v_mfma_f32_16x16x32_bf16 v[112:115], v[156:159], v[164:167], v[112:115]
	v_mfma_f32_16x16x32_bf16 v[100:103], v[148:151], v[172:175], v[100:103]
	v_mfma_f32_16x16x32_bf16 v[96:99], v[156:159], v[172:175], v[96:99]
	v_mfma_f32_16x16x32_bf16 v[84:87], v[148:151], v[180:183], v[84:87]
	v_mfma_f32_16x16x32_bf16 v[80:83], v[156:159], v[180:183], v[80:83]
	v_mfma_f32_16x16x32_bf16 v[68:71], v[148:151], v[188:191], v[68:71]
	v_mfma_f32_16x16x32_bf16 v[64:67], v[156:159], v[188:191], v[64:67]
	s_setprio 0
	s_barrier
	s_add_i32 s28, s44, s21
	v_lshl_add_u64 v[194:195], v[194:195], 0, s[48:49]
	s_mov_b32 m0, s28
	ds_read_b128 v[160:163], v243 offset:49152
	ds_read_b128 v[164:167], v243 offset:50176
	ds_read_b128 v[168:171], v243 offset:51200
	ds_read_b128 v[172:175], v243 offset:52224
	ds_read_b128 v[176:179], v243 offset:53248
	ds_read_b128 v[180:183], v243 offset:54272
	ds_read_b128 v[184:187], v243 offset:55296
	ds_read_b128 v[188:191], v243 offset:56320
	global_load_lds_dwordx4 v[194:195], off
	v_lshl_add_u64 v[194:195], v[196:197], 0, s[48:49]
	s_add_i32 m0, s28, 0x2000
	s_add_i32 s28, s45, s21
	global_load_lds_dwordx4 v[194:195], off
	v_lshl_add_u64 v[194:195], v[198:199], 0, s[48:49]
	s_mov_b32 m0, s28
	s_nop 0
	global_load_lds_dwordx4 v[194:195], off
	v_lshl_add_u64 v[194:195], v[200:201], 0, s[48:49]
	s_add_i32 m0, s28, 0x2000
	s_nop 0
	global_load_lds_dwordx4 v[194:195], off
	v_lshl_add_u64 v[194:195], v[214:215], 0, s[48:49]
	s_mov_b32 m0, s66
	s_nop 0
	global_load_lds_dwordx4 v[194:195], off
	v_lshl_add_u64 v[194:195], v[216:217], 0, s[48:49]
	s_mov_b32 m0, s67
	s_nop 0
	global_load_lds_dwordx4 v[194:195], off
	s_waitcnt vmcnt(8)
	s_waitcnt lgkmcnt(0)
	s_barrier
	s_setprio 1
	s_waitcnt lgkmcnt(0)
	v_mfma_f32_16x16x32_bf16 v[60:63], v[128:131], v[160:163], v[60:63]
	v_mfma_f32_16x16x32_bf16 v[56:59], v[136:139], v[160:163], v[56:59]
	v_mfma_f32_16x16x32_bf16 v[44:47], v[128:131], v[168:171], v[44:47]
	v_mfma_f32_16x16x32_bf16 v[40:43], v[136:139], v[168:171], v[40:43]
	v_mfma_f32_16x16x32_bf16 v[28:31], v[128:131], v[176:179], v[28:31]
	v_mfma_f32_16x16x32_bf16 v[24:27], v[136:139], v[176:179], v[24:27]
	v_mfma_f32_16x16x32_bf16 v[12:15], v[128:131], v[184:187], v[12:15]
	v_mfma_f32_16x16x32_bf16 v[8:11], v[136:139], v[184:187], v[8:11]
	v_mfma_f32_16x16x32_bf16 v[60:63], v[132:135], v[164:167], v[60:63]
	v_mfma_f32_16x16x32_bf16 v[56:59], v[140:143], v[164:167], v[56:59]
	v_mfma_f32_16x16x32_bf16 v[44:47], v[132:135], v[172:175], v[44:47]
	v_mfma_f32_16x16x32_bf16 v[40:43], v[140:143], v[172:175], v[40:43]
	v_mfma_f32_16x16x32_bf16 v[28:31], v[132:135], v[180:183], v[28:31]
	v_mfma_f32_16x16x32_bf16 v[24:27], v[140:143], v[180:183], v[24:27]
	v_mfma_f32_16x16x32_bf16 v[12:15], v[132:135], v[188:191], v[12:15]
	v_mfma_f32_16x16x32_bf16 v[8:11], v[140:143], v[188:191], v[8:11]
	s_setprio 0
	s_setprio 1
	v_mfma_f32_16x16x32_bf16 v[52:55], v[144:147], v[160:163], v[52:55]
	v_mfma_f32_16x16x32_bf16 v[48:51], v[152:155], v[160:163], v[48:51]
	v_mfma_f32_16x16x32_bf16 v[36:39], v[144:147], v[168:171], v[36:39]
	v_mfma_f32_16x16x32_bf16 v[32:35], v[152:155], v[168:171], v[32:35]
	v_mfma_f32_16x16x32_bf16 v[20:23], v[144:147], v[176:179], v[20:23]
	v_mfma_f32_16x16x32_bf16 v[16:19], v[152:155], v[176:179], v[16:19]
	v_mfma_f32_16x16x32_bf16 v[4:7], v[144:147], v[184:187], v[4:7]
	v_mfma_f32_16x16x32_bf16 v[0:3], v[152:155], v[184:187], v[0:3]
	v_mfma_f32_16x16x32_bf16 v[52:55], v[148:151], v[164:167], v[52:55]
	v_mfma_f32_16x16x32_bf16 v[48:51], v[156:159], v[164:167], v[48:51]
	v_mfma_f32_16x16x32_bf16 v[36:39], v[148:151], v[172:175], v[36:39]
	v_mfma_f32_16x16x32_bf16 v[32:35], v[156:159], v[172:175], v[32:35]
	v_mfma_f32_16x16x32_bf16 v[20:23], v[148:151], v[180:183], v[20:23]
	v_mfma_f32_16x16x32_bf16 v[16:19], v[156:159], v[180:183], v[16:19]
	v_mfma_f32_16x16x32_bf16 v[4:7], v[148:151], v[188:191], v[4:7]
	v_mfma_f32_16x16x32_bf16 v[0:3], v[156:159], v[188:191], v[0:3]
	s_setprio 0
	s_barrier
	s_add_u32 s2, s2, 0x100
	s_addc_u32 s3, s3, 0
	s_add_u32 s34, s34, 0x100
	s_addc_u32 s35, s35, 0
	s_cmp_ge_u32 s43, s65
	s_mov_b32 s28, s43

.LBB0_626:
	v_and_b32_e32 v182, 31, v32
	v_or_b32_e32 v174, s70, v182
	v_add_u32_e32 v186, s20, v174
	s_add_i32 s23, s70, s20
	s_lshl_b32 s20, s2, 12
	s_add_i32 s0, s20, 0x18800
	v_lshrrev_b32_e32 v183, 5, v192
	s_cmp_lt_i32 s2, 7
	v_lshlrev_b32_e32 v0, 10, v183
	v_lshlrev_b32_e32 v1, 4, v182
	s_cselect_b32 s33, s0, 0x20100
	v_add3_u32 v177, 0, v0, v1
	s_add_i32 s0, s33, 0
	v_lshlrev_b32_e32 v0, 7, v182
	v_lshlrev_b32_e32 v1, 4, v183
	v_add3_u32 v0, s0, v0, v1
	ds_read_b128 v[124:127], v0
	ds_read_b128 v[120:123], v0 offset:32
	ds_read_b128 v[112:115], v0 offset:64
	ds_read_b128 v[104:107], v0 offset:96
	s_waitcnt lgkmcnt(0)
	s_cmpk_ge_i32 s23, 0xc0
	s_cbranch_scc1 .Lxs_idle
	ds_read_b128 v[0:3], v177
	ds_read_b128 v[4:7], v177 offset:512
	s_waitcnt lgkmcnt(1)
	v_mfma_f32_32x32x16_bf16 v[16:31], v[0:3], v[124:127], 0
	ds_read_b128 v[34:37], v177 offset:2048
	ds_read_b128 v[38:41], v177 offset:2560
	v_lshlrev_b32_e32 v184, 2, v183
	s_cmp_gt_i32 s23, 62
	v_or_b32_e32 v62, 32, v184
	v_or_b32_e32 v61, 33, v184
	v_or_b32_e32 v59, 2, v184
	v_or_b32_e32 v60, 34, v184
	s_waitcnt lgkmcnt(2)
	v_mfma_f32_32x32x16_bf16 v[0:15], v[4:7], v[124:127], 0
	v_or_b32_e32 v57, 3, v184
	v_or_b32_e32 v58, 35, v184
	v_or_b32_e32 v55, 8, v184
	v_or_b32_e32 v56, 40, v184
	v_or_b32_e32 v53, 9, v184
	v_or_b32_e32 v54, 41, v184
	v_or_b32_e32 v51, 10, v184
	s_waitcnt lgkmcnt(1)
	v_mfma_f32_32x32x16_bf16 v[16:31], v[34:37], v[120:123], v[16:31]
	v_or_b32_e32 v52, 42, v184
	v_or_b32_e32 v49, 11, v184
	v_or_b32_e32 v50, 43, v184
	v_or_b32_e32 v47, 16, v184
	v_or_b32_e32 v48, 48, v184
	v_or_b32_e32 v45, 17, v184
	v_or_b32_e32 v46, 49, v184
	s_waitcnt lgkmcnt(0)
	v_mfma_f32_32x32x16_bf16 v[0:15], v[38:41], v[120:123], v[0:15]
	ds_read_b128 v[34:37], v177 offset:4096
	ds_read_b128 v[38:41], v177 offset:4608
	v_or_b32_e32 v43, 18, v184
	v_or_b32_e32 v44, 50, v184
	v_or_b32_e32 v42, 51, v184
	v_or_b32_e32 v33, 27, v184
	s_waitcnt lgkmcnt(1)
	v_mfma_f32_32x32x16_bf16 v[16:31], v[34:37], v[112:115], v[16:31]
	s_waitcnt lgkmcnt(0)
	v_mfma_f32_32x32x16_bf16 v[0:15], v[38:41], v[112:115], v[0:15]
	ds_read_b128 v[34:37], v177 offset:6144
	ds_read_b128 v[38:41], v177 offset:6656
	s_waitcnt lgkmcnt(1)
	v_mfma_f32_32x32x16_bf16 v[16:31], v[34:37], v[104:107], v[16:31]
	v_or_b32_e32 v37, 25, v184
	v_or_b32_e32 v35, 26, v184
	v_or_b32_e32 v36, 58, v184
	v_or_b32_e32 v34, 59, v184
	s_waitcnt lgkmcnt(0)
	v_mfma_f32_32x32x16_bf16 v[0:15], v[38:41], v[104:107], v[0:15]
	v_or_b32_e32 v41, 19, v184
	v_or_b32_e32 v39, 24, v184
	v_or_b32_e32 v40, 56, v184
	v_or_b32_e32 v38, 57, v184
	s_nop 15
	s_nop 7
	s_cbranch_scc1 .LBB0_630
	v_cmp_le_i32_e64 s[0:1], v62, v186
	v_cmp_le_i32_e64 s[38:39], v61, v186
	v_cmp_le_i32_e64 s[40:41], v60, v186
	v_cmp_le_i32_e64 s[42:43], v58, v186
	v_cmp_le_i32_e64 s[44:45], v56, v186
	v_cmp_le_i32_e64 s[46:47], v54, v186
	v_cmp_le_i32_e64 s[50:51], v52, v186
	v_cmp_le_i32_e64 s[52:53], v50, v186
	v_cmp_le_i32_e64 s[54:55], v48, v186
	v_cmp_le_i32_e64 s[56:57], v46, v186
	v_cmp_le_i32_e64 s[58:59], v44, v186
	v_cmp_le_i32_e64 s[60:61], v42, v186
	v_cmp_le_i32_e64 s[62:63], v40, v186
	v_cmp_le_i32_e64 s[64:65], v38, v186
	v_cmp_le_i32_e64 s[66:67], v36, v186
	v_cmp_le_i32_e32 vcc, v184, v186
	v_cndmask_b32_e64 v0, v240, v0, s[0:1]
	v_cmp_lt_i32_e64 s[0:1], v184, v186
	v_cndmask_b32_e64 v1, v240, v1, s[38:39]
	v_cmp_le_i32_e64 s[38:39], v59, v186
	v_cndmask_b32_e64 v2, v240, v2, s[40:41]
	v_cmp_le_i32_e64 s[40:41], v57, v186
	v_cndmask_b32_e64 v3, v240, v3, s[42:43]
	v_cmp_le_i32_e64 s[42:43], v55, v186
	v_cndmask_b32_e64 v4, v240, v4, s[44:45]
	v_cmp_le_i32_e64 s[44:45], v53, v186
	v_cndmask_b32_e64 v5, v240, v5, s[46:47]
	v_cmp_le_i32_e64 s[46:47], v51, v186
	v_cndmask_b32_e64 v6, v240, v6, s[50:51]
	v_cmp_le_i32_e64 s[50:51], v49, v186
	v_cndmask_b32_e64 v7, v240, v7, s[52:53]
	v_cmp_le_i32_e64 s[52:53], v47, v186
	v_cndmask_b32_e64 v8, v240, v8, s[54:55]
	v_cmp_le_i32_e64 s[54:55], v45, v186
	v_cndmask_b32_e64 v9, v240, v9, s[56:57]
	v_cmp_le_i32_e64 s[56:57], v43, v186
	v_cndmask_b32_e64 v10, v240, v10, s[58:59]
	v_cmp_le_i32_e64 s[58:59], v41, v186
	v_cndmask_b32_e64 v11, v240, v11, s[60:61]
	v_cmp_le_i32_e64 s[60:61], v39, v186
	v_cndmask_b32_e64 v12, v240, v12, s[62:63]
	v_cmp_le_i32_e64 s[62:63], v37, v186
	v_cndmask_b32_e64 v13, v240, v13, s[64:65]
	v_cmp_le_i32_e64 s[64:65], v35, v186
	v_cndmask_b32_e64 v14, v240, v14, s[66:67]
	v_cmp_le_i32_e64 s[66:67], v33, v186
	v_cmp_gt_i32_e64 s[68:69], v34, v186
	s_and_saveexec_b64 s[2:3], s[68:69]
	s_mov_b32 s4, 0xff800000
	v_mov_b32_e32 v15, s4
	s_or_b64 exec, exec, s[2:3]
	v_cndmask_b32_e64 v17, v240, v17, s[0:1]
	v_cndmask_b32_e32 v16, v240, v16, vcc
	v_cndmask_b32_e64 v18, v240, v18, s[38:39]
	v_cndmask_b32_e64 v19, v240, v19, s[40:41]
	v_cndmask_b32_e64 v20, v240, v20, s[42:43]
	v_cndmask_b32_e64 v21, v240, v21, s[44:45]
	v_cndmask_b32_e64 v22, v240, v22, s[46:47]
	v_cndmask_b32_e64 v23, v240, v23, s[50:51]
	v_cndmask_b32_e64 v24, v240, v24, s[52:53]
	v_cndmask_b32_e64 v25, v240, v25, s[54:55]
	v_cndmask_b32_e64 v26, v240, v26, s[56:57]
	v_cndmask_b32_e64 v27, v240, v27, s[58:59]
	v_cndmask_b32_e64 v28, v240, v28, s[60:61]
	v_cndmask_b32_e64 v29, v240, v29, s[62:63]
	v_cndmask_b32_e64 v30, v240, v30, s[64:65]
	v_cndmask_b32_e64 v31, v240, v31, s[66:67]

.Lxs_idle:
	v_lshlrev_b32_e32 v184, 2, v183
	v_add_u32_e32 v187, 0xffffff80, v186
	v_mov_b32_e32 v0, v240
	v_mov_b32_e32 v1, v240
	v_mov_b32_e32 v2, v240
	v_mov_b32_e32 v3, v240
	v_mov_b32_e32 v4, v240
	v_mov_b32_e32 v5, v240
	v_mov_b32_e32 v6, v240
	v_mov_b32_e32 v7, v240
	v_mov_b32_e32 v8, v240
	v_mov_b32_e32 v9, v240
	v_mov_b32_e32 v10, v240
	v_mov_b32_e32 v11, v240
	v_mov_b32_e32 v12, v240
	v_mov_b32_e32 v13, v240
	v_mov_b32_e32 v14, v240
	v_mov_b32_e32 v15, v240
	v_mov_b32_e32 v16, v240
	v_mov_b32_e32 v17, v240
	v_mov_b32_e32 v18, v240
	v_mov_b32_e32 v19, v240
	v_mov_b32_e32 v20, v240
	v_mov_b32_e32 v21, v240
	v_mov_b32_e32 v22, v240
	v_mov_b32_e32 v23, v240
	v_mov_b32_e32 v24, v240
	v_mov_b32_e32 v25, v240
	v_mov_b32_e32 v26, v240
	v_mov_b32_e32 v27, v240
	v_mov_b32_e32 v28, v240
	v_mov_b32_e32 v29, v240
	v_mov_b32_e32 v30, v240
	v_mov_b32_e32 v31, v240
	s_branch .LBB0_634

.LBB0_759:
	v_mov_b32_e32 v34, v230
	v_and_b32_e32 v164, 63, v34
	v_readfirstlane_b32 s20, v34
	s_ashr_i32 s21, s20, 6
	v_lshlrev_b32_e32 v192, 11, v164
	v_lshl_add_u64 v[0:1], s[26:27], 0, v[192:193]
	s_lshl_b32 s26, s21, 3
	s_ashr_i32 s27, s26, 31
	v_lshl_add_u64 v[32:33], s[26:27], 1, v[0:1]
	s_lshl_b32 s0, s21, 4
	v_bfe_u32 v0, v34, 2, 4
	v_and_or_b32 v0, s0, 48, v0
	s_ashr_i32 s0, s20, 3
	v_lshlrev_b32_e32 v192, 11, v0
	s_andn2_b32 s0, s0, 31
	s_lshl_b32 s70, s21, 5
	v_lshl_add_u64 v[0:1], s[18:19], 0, v[192:193]
	s_ashr_i32 s1, s0, 31
	v_lshlrev_b32_e32 v163, 3, v34
	s_lshl_b32 s19, s21, 10
	v_and_b32_e32 v168, 24, v163
	s_cmp_lg_u32 0, -1
	v_lshl_add_u64 v[0:1], s[0:1], 1, v[0:1]
	v_lshlrev_b32_e32 v192, 1, v168
	s_cselect_b32 s0, 0, 0
	v_lshl_add_u64 v[72:73], v[0:1], 0, v[192:193]
	s_add_i32 s22, s19, s0
	v_lshrrev_b32_e32 v162, 3, v164
	v_and_b32_e32 v0, 56, v163
	s_add_i32 s33, s22, 0x6000
	s_mov_b64 s[0:1], -1
	s_and_b64 vcc, exec, s[38:39]
	v_or_b32_e32 v160, s70, v162
	v_lshlrev_b32_e32 v192, 1, v0
	s_cbranch_vccz .LBB0_803
	s_andn2_b64 vcc, exec, s[0:1]
	s_cbranch_vccz .LBB0_804
